# kvprep (depends only on the P3 ckv partials) moved from P6 into the memory-bound half of P4 so it overlaps other CUs' ssd_out
# speedup vs baseline: 1.0031x; 1.0018x over previous
.LBB0_1003:
	s_or_b64 exec, exec, s[2:3]
.Lmy_kv_begin:
	s_waitcnt lgkmcnt(0)
	v_lshl_add_u32 v10, s33, 3, v159
	s_movk_i32 s0, 0x1000
	v_cmp_gt_i32_e32 vcc, s0, v10
	s_and_saveexec_b64 s[0:1], vcc
	s_cbranch_execz .Lmy_kv_end
	v_mbcnt_lo_u32_b32 v2, -1, 0
	v_mbcnt_hi_u32_b32 v2, -1, v2
	v_and_b32_e32 v3, 64, v2
	v_add_u32_e32 v3, 64, v3
	v_xor_b32_e32 v4, 1, v2
	v_cmp_lt_i32_e32 vcc, v4, v3
	v_lshlrev_b32_e32 v0, 1, v158
	v_and_b32_e32 v8, 0x7e, v0
	v_cndmask_b32_e32 v4, v2, v4, vcc
	v_lshlrev_b32_e32 v11, 2, v4
	v_xor_b32_e32 v4, 2, v2
	v_cmp_lt_i32_e32 vcc, v4, v3
	v_readlane_b32 s12, v252, 23
	v_mov_b32_e32 v1, 0
	v_cndmask_b32_e32 v4, v2, v4, vcc
	v_lshlrev_b32_e32 v12, 2, v4
	v_xor_b32_e32 v4, 4, v2
	v_cmp_lt_i32_e32 vcc, v4, v3
	v_lshlrev_b32_e32 v0, 2, v8
	v_readlane_b32 s20, v252, 31
	v_cndmask_b32_e32 v4, v2, v4, vcc
	v_lshlrev_b32_e32 v13, 2, v4
	v_xor_b32_e32 v4, 8, v2
	v_cmp_lt_i32_e32 vcc, v4, v3
	v_readlane_b32 s21, v252, 32
	s_add_u32 s2, s84, 0x5088000
	v_cndmask_b32_e32 v4, v2, v4, vcc
	v_lshlrev_b32_e32 v14, 2, v4
	v_xor_b32_e32 v4, 16, v2
	v_cmp_lt_i32_e32 vcc, v4, v3
	v_lshl_add_u64 v[6:7], s[84:85], 0, v[0:1]
	v_bfe_u32 v17, v158, 6, 2
	v_cndmask_b32_e32 v4, v2, v4, vcc
	v_lshlrev_b32_e32 v15, 2, v4
	v_xor_b32_e32 v4, 32, v2
	v_cmp_lt_i32_e32 vcc, v4, v3
	s_addc_u32 s3, s85, 0
	s_mov_b64 s[6:7], 0x5800000
	v_cndmask_b32_e32 v2, v2, v4, vcc
	v_lshlrev_b32_e32 v16, 2, v2
	v_lshl_add_u64 v[2:3], s[20:21], 0, v[0:1]
	v_lshlrev_b32_e32 v0, 9, v8
	v_lshl_add_u64 v[4:5], s[84:85], 0, v[0:1]
	v_lshlrev_b32_e32 v0, 9, v17
	s_add_u32 s4, s84, 0x5700000
	v_lshl_add_u64 v[4:5], v[4:5], 0, s[6:7]
	v_lshl_add_u64 v[6:7], v[6:7], 0, v[0:1]
	s_mov_b64 s[6:7], 0x8c00000
	s_addc_u32 s5, s85, 0
	s_lshl_b32 s8, s88, 3
	v_lshl_add_u64 v[6:7], v[6:7], 0, s[6:7]
	s_mov_b64 s[6:7], 0
	v_mov_b32_e32 v18, 0x358637bd
	s_mov_b32 s9, 0x800000
	v_lshlrev_b32_e32 v8, 1, v8
	v_mov_b32_e32 v9, v1
	s_movk_i32 s10, 0x7fff
	s_movk_i32 s11, 0xfff
	v_mov_b32_e32 v19, 8
	v_mov_b32_e32 v20, 1
	v_readlane_b32 s13, v252, 24
	v_readlane_b32 s14, v252, 25
	v_readlane_b32 s15, v252, 26
	v_readlane_b32 s16, v252, 27
	v_readlane_b32 s17, v252, 28
	v_readlane_b32 s18, v252, 29
	v_readlane_b32 s19, v252, 30
	v_readlane_b32 s22, v252, 33
	v_readlane_b32 s23, v252, 34
	v_readlane_b32 s24, v252, 35
	v_readlane_b32 s25, v252, 36
	v_readlane_b32 s26, v252, 37
	v_readlane_b32 s27, v252, 38

.Lmy_kv_end:
	s_or_b64 exec, exec, s[0:1]
	s_cmp_eq_u32 s70, 0
	s_cbranch_scc0 .Lmy_p4_done
	s_mov_b32 s70, 1
	s_waitcnt vmcnt(0) lgkmcnt(0)
	s_branch .Lmy_p4_pre

.LBB0_1183:
.LBB0_1186:
	s_cmp_lt_i32 s87, 8
	s_cbranch_scc1 .LBB0_1240
	s_waitcnt vmcnt(0)
	s_waitcnt vmcnt(0)
	s_barrier
	s_mov_b64 s[0:1], exec
	v_readlane_b32 s2, v252, 5
	v_readlane_b32 s3, v252, 6
	s_and_b64 s[2:3], s[0:1], s[2:3]
	s_mov_b64 exec, s[2:3]
	s_cbranch_execz .LBB0_1239
	s_add_i32 s2, 0, 0x25fc0
	v_mov_b32_e32 v0, s2
	s_waitcnt vmcnt(0) expcnt(0) lgkmcnt(0)
	ds_read_b32 v2, v0
	s_add_i32 s2, 0, 0x25fc4
	v_mov_b32_e32 v0, s2
	ds_read_b32 v0, v0
	s_waitcnt lgkmcnt(1)
	v_cmp_ne_u32_e32 vcc, 0, v2
	s_cbranch_vccnz .LBB0_1203
	v_readlane_b32 s2, v252, 0
	v_readlane_b32 s3, v252, 1
	s_load_dwordx2 s[6:7], s[2:3], 0x4
	s_add_u32 s2, s84, 0x5900200
	s_addc_u32 s3, s85, 0
	s_add_u32 s4, s84, 0x5900400
	s_addc_u32 s5, s85, 0
	s_waitcnt lgkmcnt(0)
	s_mul_i32 s44, s6, s88
	s_add_u32 s6, s84, 0x5900500
	s_mul_i32 s44, s44, s7
	s_addc_u32 s7, s85, 0
	s_add_u32 s8, s84, 0x5900600
	s_addc_u32 s9, s85, 0
	s_add_u32 s10, s84, 0x5900700
	s_addc_u32 s11, s85, 0
	s_add_u32 s12, s84, 0x5900800
	s_addc_u32 s13, s85, 0
	s_add_u32 s14, s84, 0x5900900
	s_addc_u32 s15, s85, 0
	s_add_u32 s16, s84, 0x5900a00
	s_addc_u32 s17, s85, 0
	s_add_u32 s18, s84, 0x5900b00
	s_addc_u32 s19, s85, 0
	s_add_u32 s20, s84, 0x5900c00
	s_addc_u32 s21, s85, 0
	s_add_u32 s22, s84, 0x5900d00
	s_addc_u32 s23, s85, 0
	s_add_u32 s24, s84, 0x5900e00
	s_addc_u32 s25, s85, 0
	s_add_u32 s26, s84, 0x5900f00
	s_addc_u32 s27, s85, 0
	s_add_u32 s28, s84, 0x5901000
	s_addc_u32 s29, s85, 0
	s_add_u32 s30, s84, 0x5901100
	s_addc_u32 s31, s85, 0
	s_add_u32 s34, s84, 0x5901200
	s_addc_u32 s35, s85, 0
	s_add_u32 s36, s84, 0x5901300
	s_addc_u32 s37, s85, 0
	s_mov_b32 s45, 1
	v_mov_b32_e32 v16, 0
	s_branch .LBB0_1191
